# MoBA P masking via EXEC-masked cvt over pre-zeroed regs; MODE1 finish uses base+offset LDS addressing
# baseline (speedup 1.0000x reference)
.LBB0_346:
	s_lshl_b32 s12, s66, 2
	s_add_i32 s13, s12, 4
	s_and_b64 s[10:11], exec, s[52:53]
	s_cselect_b32 s69, s13, s67
	s_cmp_ge_u32 s12, s69
	s_cbranch_scc1 .LBB0_379
	s_andn2_b64 s[10:11], exec, s[6:7]
	s_cbranch_scc0 .Lm_nozero
	s_mov_b64 exec, s[10:11]
	v_mov_b32_e32 v144, 0
	v_mov_b32_e32 v145, 0
	v_mov_b32_e32 v146, 0
	v_mov_b32_e32 v147, 0
	v_mov_b32_e32 v148, 0
	v_mov_b32_e32 v149, 0
	v_mov_b32_e32 v150, 0
	v_mov_b32_e32 v151, 0
	v_mov_b32_e32 v152, 0
	v_mov_b32_e32 v153, 0
	v_mov_b32_e32 v154, 0
	v_mov_b32_e32 v155, 0
	v_mov_b32_e32 v156, 0
	v_mov_b32_e32 v157, 0
	v_mov_b32_e32 v158, 0
	v_mov_b32_e32 v159, 0
	s_mov_b64 exec, -1
.Lm_nozero:
	ds_read_b128 v[32:35], v176
	ds_read_b128 v[48:51], v176 offset:512
	ds_read_b128 v[64:67], v176 offset:2080
	ds_read_b128 v[68:71], v176 offset:2592
	s_xor_b64 s[10:11], s[52:53], -1
	s_nor_b64 s[54:55], s[10:11], s[8:9]
	s_waitcnt lgkmcnt(3)
	v_mfma_f32_32x32x16_bf16 v[32:47], v[32:35], v[128:131], 0
	v_mov_b32_e32 v178, v173
	s_mov_b32 s70, s68
	s_mov_b32 s71, s65
	v_mov_b32_e32 v179, v172
	s_waitcnt lgkmcnt(2)
	v_mfma_f32_32x32x16_bf16 v[48:63], v[48:51], v[128:131], 0
	s_waitcnt lgkmcnt(1)
	v_mfma_f32_32x32x16_bf16 v[32:47], v[64:67], v[132:135], v[32:47]
	s_waitcnt lgkmcnt(0)
	v_mfma_f32_32x32x16_bf16 v[48:63], v[68:71], v[132:135], v[48:63]
	ds_read_b128 v[64:67], v176 offset:4160
	ds_read_b128 v[68:71], v176 offset:4672
	s_waitcnt lgkmcnt(1)
	v_mfma_f32_32x32x16_bf16 v[32:47], v[64:67], v[136:139], v[32:47]
	s_waitcnt lgkmcnt(0)
	v_mfma_f32_32x32x16_bf16 v[48:63], v[68:71], v[136:139], v[48:63]
	ds_read_b128 v[64:67], v176 offset:6240
	ds_read_b128 v[68:71], v176 offset:6752
	s_waitcnt lgkmcnt(1)
	v_mfma_f32_32x32x16_bf16 v[32:47], v[64:67], v[140:143], v[32:47]
	s_waitcnt lgkmcnt(0)
	v_mfma_f32_32x32x16_bf16 v[48:63], v[68:71], v[140:143], v[48:63]
	s_branch .LBB0_349
.Lm_fastA:
	ds_read_b128 v[196:199], v179
	ds_read_b128 v[200:203], v179 offset:512
	ds_read_b128 v[204:207], v179 offset:2080
	ds_read_b128 v[208:211], v179 offset:2592
	ds_read_b128 v[212:215], v179 offset:4160
	ds_read_b128 v[216:219], v179 offset:4672
	ds_read_b128 v[188:191], v179 offset:6240
	ds_read_b128 v[224:227], v179 offset:6752
	v_max_f32_e32 v238, v32, v32
	v_max_f32_e32 v239, v48, v48
	v_max3_f32 v238, v238, v33, v34
	v_max3_f32 v239, v239, v49, v50
	v_max3_f32 v238, v238, v35, v36
	s_waitcnt lgkmcnt(7)
	v_mfma_f32_32x32x16_bf16 v[64:79], v[196:199], v[128:131], 0
	v_max3_f32 v239, v239, v51, v52
	v_max3_f32 v238, v238, v37, v38
	v_max3_f32 v239, v239, v53, v54
	v_max3_f32 v238, v238, v39, v40
	s_waitcnt lgkmcnt(6)
	v_mfma_f32_32x32x16_bf16 v[80:95], v[200:203], v[128:131], 0
	v_max3_f32 v239, v239, v55, v56
	v_max3_f32 v238, v238, v41, v42
	v_max3_f32 v239, v239, v57, v58
	v_max3_f32 v238, v238, v43, v44
	s_waitcnt lgkmcnt(5)
	v_mfma_f32_32x32x16_bf16 v[64:79], v[204:207], v[132:135], v[64:79]
	v_max3_f32 v239, v239, v59, v60
	v_max3_f32 v238, v238, v45, v46
	v_max3_f32 v239, v239, v61, v62
	s_waitcnt lgkmcnt(4)
	v_mfma_f32_32x32x16_bf16 v[80:95], v[208:211], v[132:135], v[80:95]
	v_max3_f32 v238, v238, v47, v63
	v_max_f32_e32 v238, v238, v239
	v_mov_b32_e32 v239, v238
	s_nop 1
	v_permlane32_swap_b32_e32 v238, v239
	v_max_f32_e32 v238, v238, v239
	v_cmp_lt_f32_e32 vcc, s1, v238
	s_cbranch_vccnz .Lm_rareA
	s_waitcnt lgkmcnt(0)
	ds_read_b64_tr_b16 v[196:197], v178 offset:49920
	ds_read_b64_tr_b16 v[198:199], v178 offset:50432
	ds_read_b64_tr_b16 v[200:201], v178 offset:54016
	ds_read_b64_tr_b16 v[202:203], v178 offset:54528
	ds_read_b64_tr_b16 v[204:205], v178 offset:50944
	ds_read_b64_tr_b16 v[206:207], v178 offset:51456
	ds_read_b64_tr_b16 v[208:209], v178 offset:55040
	ds_read_b64_tr_b16 v[210:211], v178 offset:55552
	v_exp_f32_e32 v32, v32
	v_exp_f32_e32 v48, v48
	v_exp_f32_e32 v33, v33
	v_exp_f32_e32 v49, v49
	v_mfma_f32_32x32x16_bf16 v[64:79], v[212:215], v[136:139], v[64:79]
	v_exp_f32_e32 v34, v34
	v_exp_f32_e32 v50, v50
	v_exp_f32_e32 v35, v35
	v_exp_f32_e32 v51, v51
	v_exp_f32_e32 v36, v36
	v_exp_f32_e32 v52, v52
	v_mfma_f32_32x32x16_bf16 v[80:95], v[216:219], v[136:139], v[80:95]
	v_exp_f32_e32 v37, v37
	v_exp_f32_e32 v53, v53
	v_exp_f32_e32 v38, v38
	v_exp_f32_e32 v54, v54
	v_exp_f32_e32 v39, v39
	v_exp_f32_e32 v55, v55
	v_mfma_f32_32x32x16_bf16 v[64:79], v[188:191], v[140:143], v[64:79]
	v_exp_f32_e32 v40, v40
	v_exp_f32_e32 v56, v56
	v_exp_f32_e32 v41, v41
	v_exp_f32_e32 v57, v57
	v_exp_f32_e32 v42, v42
	v_exp_f32_e32 v58, v58
	v_mfma_f32_32x32x16_bf16 v[80:95], v[224:227], v[140:143], v[80:95]
	v_exp_f32_e32 v43, v43
	v_exp_f32_e32 v59, v59
	v_exp_f32_e32 v44, v44
	v_exp_f32_e32 v60, v60
	v_exp_f32_e32 v45, v45
	v_exp_f32_e32 v61, v61
	v_exp_f32_e32 v46, v46
	v_exp_f32_e32 v62, v62
	v_exp_f32_e32 v47, v47
	v_exp_f32_e32 v63, v63
	s_waitcnt lgkmcnt(7)
	ds_read_b64_tr_b16 v[212:213], v178 offset:51968
	ds_read_b64_tr_b16 v[214:215], v178 offset:52480
	ds_read_b64_tr_b16 v[216:217], v178 offset:56064
	ds_read_b64_tr_b16 v[218:219], v178 offset:56576
	ds_read_b64_tr_b16 v[188:189], v178 offset:52992
	ds_read_b64_tr_b16 v[190:191], v178 offset:53504
	ds_read_b64_tr_b16 v[224:225], v178 offset:57088
	ds_read_b64_tr_b16 v[226:227], v178 offset:57600
	v_pk_add_f32 v[238:239], v[52:53], v[36:37]
	v_pk_add_f32 v[240:241], v[48:49], v[32:33]
	v_pk_add_f32 v[242:243], v[54:55], v[38:39]
	v_pk_add_f32 v[244:245], v[50:51], v[34:35]
	s_mov_b64 exec, s[6:7]
	v_cvt_pk_bf16_f32 v156, v32, v33
	v_cvt_pk_bf16_f32 v157, v34, v35
	v_cvt_pk_bf16_f32 v158, v36, v37
	v_cvt_pk_bf16_f32 v159, v38, v39
	s_mov_b64 exec, -1
	v_pk_add_f32 v[246:247], v[58:59], v[42:43]
	v_pk_add_f32 v[248:249], v[56:57], v[40:41]
	s_waitcnt lgkmcnt(14)
	v_mfma_f32_32x32x16_bf16 v[16:31], v[156:159], v[196:199], v[16:31]
	v_pk_add_f32 v[242:243], v[244:245], v[242:243]
	v_pk_add_f32 v[238:239], v[240:241], v[238:239]
	s_mov_b64 exec, s[6:7]
	v_cvt_pk_bf16_f32 v152, v40, v41
	v_cvt_pk_bf16_f32 v153, v42, v43
	v_cvt_pk_bf16_f32 v154, v44, v45
	v_cvt_pk_bf16_f32 v155, v46, v47
	s_mov_b64 exec, -1
	s_waitcnt lgkmcnt(12)
	v_mfma_f32_32x32x16_bf16 v[0:15], v[156:159], v[200:203], v[0:15]
	v_pk_add_f32 v[240:241], v[60:61], v[44:45]
	v_pk_add_f32 v[244:245], v[62:63], v[46:47]
	s_waitcnt lgkmcnt(10)
	v_mfma_f32_32x32x16_bf16 v[16:31], v[152:155], v[204:207], v[16:31]
	v_pk_add_f32 v[248:249], v[248:249], v[238:239]
	v_pk_add_f32 v[246:247], v[246:247], v[242:243]
	s_mov_b64 exec, s[6:7]
	v_cvt_pk_bf16_f32 v148, v48, v49
	v_cvt_pk_bf16_f32 v149, v50, v51
	v_cvt_pk_bf16_f32 v150, v52, v53
	v_cvt_pk_bf16_f32 v151, v54, v55
	s_mov_b64 exec, -1
	s_waitcnt lgkmcnt(8)
	v_mfma_f32_32x32x16_bf16 v[0:15], v[152:155], v[208:211], v[0:15]
	v_pk_add_f32 v[182:183], v[240:241], v[248:249]
	v_pk_add_f32 v[180:181], v[244:245], v[246:247]
	s_waitcnt lgkmcnt(6)
	v_mfma_f32_32x32x16_bf16 v[16:31], v[148:151], v[212:215], v[16:31]
	v_pk_mov_b32 v[184:185], v[182:183], v[180:181] op_sel:[1,0]
	v_mov_b32_e32 v183, v181
	s_mov_b64 exec, s[6:7]
	v_cvt_pk_bf16_f32 v144, v56, v57
	v_cvt_pk_bf16_f32 v145, v58, v59
	v_cvt_pk_bf16_f32 v146, v60, v61
	v_cvt_pk_bf16_f32 v147, v62, v63
	s_mov_b64 exec, -1
	s_waitcnt lgkmcnt(4)
	v_mfma_f32_32x32x16_bf16 v[0:15], v[148:151], v[216:219], v[0:15]
	v_pk_add_f32 v[180:181], v[184:185], v[182:183]
	s_waitcnt lgkmcnt(2)
	v_mfma_f32_32x32x16_bf16 v[16:31], v[144:147], v[188:191], v[16:31]
	v_add_f32_e32 v181, v180, v181
	v_cndmask_b32_e64 v181, 0, v181, s[6:7]
	v_add_f32_e32 v177, v177, v181
	s_waitcnt lgkmcnt(0)
	v_mfma_f32_32x32x16_bf16 v[0:15], v[144:147], v[224:227], v[0:15]
	v_add_u32_e32 v180, 0, v178
	s_andn2_b64 s[8:9], exec, s[54:55]
	s_branch .Lm_halfB
.Lm_rareA:
	v_mov_b32_e32 v144, v238
	s_waitcnt lgkmcnt(0)
	v_mfma_f32_32x32x16_bf16 v[64:79], v[212:215], v[136:139], v[64:79]
	v_mfma_f32_32x32x16_bf16 v[80:95], v[216:219], v[136:139], v[80:95]
	v_mfma_f32_32x32x16_bf16 v[64:79], v[188:191], v[140:143], v[64:79]
	v_mfma_f32_32x32x16_bf16 v[80:95], v[224:227], v[140:143], v[80:95]
	s_branch .Lm_old358
.Lm_fastB:
	v_add_u32_e32 v251, 0x10100, v178
	ds_read_b128 v[196:199], v179 offset:8320
	ds_read_b128 v[200:203], v179 offset:8832
	ds_read_b128 v[204:207], v179 offset:10400
	ds_read_b128 v[208:211], v179 offset:10912
	ds_read_b128 v[212:215], v179 offset:12480
	ds_read_b128 v[216:219], v179 offset:12992
	ds_read_b128 v[188:191], v179 offset:14560
	ds_read_b128 v[224:227], v179 offset:15072
	v_max_f32_e32 v238, v64, v64
	v_max_f32_e32 v239, v80, v80
	v_max3_f32 v238, v238, v65, v66
	v_max3_f32 v239, v239, v81, v82
	v_max3_f32 v238, v238, v67, v68
	s_waitcnt lgkmcnt(7)
	v_mfma_f32_32x32x16_bf16 v[32:47], v[196:199], v[128:131], 0
	v_max3_f32 v239, v239, v83, v84
	v_max3_f32 v238, v238, v69, v70
	v_max3_f32 v239, v239, v85, v86
	v_max3_f32 v238, v238, v71, v72
	s_waitcnt lgkmcnt(6)
	v_mfma_f32_32x32x16_bf16 v[48:63], v[200:203], v[128:131], 0
	v_max3_f32 v239, v239, v87, v88
	v_max3_f32 v238, v238, v73, v74
	v_max3_f32 v239, v239, v89, v90
	v_max3_f32 v238, v238, v75, v76
	s_waitcnt lgkmcnt(5)
	v_mfma_f32_32x32x16_bf16 v[32:47], v[204:207], v[132:135], v[32:47]
	v_max3_f32 v239, v239, v91, v92
	v_max3_f32 v238, v238, v77, v78
	v_max3_f32 v239, v239, v93, v94
	s_waitcnt lgkmcnt(4)
	v_mfma_f32_32x32x16_bf16 v[48:63], v[208:211], v[132:135], v[48:63]
	v_max3_f32 v238, v238, v79, v95
	v_max_f32_e32 v238, v238, v239
	v_mov_b32_e32 v239, v238
	s_nop 1
	v_permlane32_swap_b32_e32 v238, v239
	v_max_f32_e32 v238, v238, v239
	v_cmp_lt_f32_e32 vcc, s1, v238
	s_cbranch_vccnz .Lm_rareB
	s_waitcnt lgkmcnt(0)
	ds_read_b64_tr_b16 v[196:197], v178 offset:58112
	ds_read_b64_tr_b16 v[198:199], v178 offset:58624
	ds_read_b64_tr_b16 v[200:201], v178 offset:62208
	ds_read_b64_tr_b16 v[202:203], v178 offset:62720
	ds_read_b64_tr_b16 v[204:205], v178 offset:59136
	ds_read_b64_tr_b16 v[206:207], v178 offset:59648
	ds_read_b64_tr_b16 v[208:209], v178 offset:63232
	ds_read_b64_tr_b16 v[210:211], v178 offset:63744
	v_exp_f32_e32 v64, v64
	v_exp_f32_e32 v80, v80
	v_exp_f32_e32 v65, v65
	v_exp_f32_e32 v81, v81
	v_mfma_f32_32x32x16_bf16 v[32:47], v[212:215], v[136:139], v[32:47]
	v_exp_f32_e32 v66, v66
	v_exp_f32_e32 v82, v82
	v_exp_f32_e32 v67, v67
	v_exp_f32_e32 v83, v83
	v_exp_f32_e32 v68, v68
	v_exp_f32_e32 v84, v84
	v_mfma_f32_32x32x16_bf16 v[48:63], v[216:219], v[136:139], v[48:63]
	v_exp_f32_e32 v69, v69
	v_exp_f32_e32 v85, v85
	v_exp_f32_e32 v70, v70
	v_exp_f32_e32 v86, v86
	v_exp_f32_e32 v71, v71
	v_exp_f32_e32 v87, v87
	v_mfma_f32_32x32x16_bf16 v[32:47], v[188:191], v[140:143], v[32:47]
	v_exp_f32_e32 v72, v72
	v_exp_f32_e32 v88, v88
	v_exp_f32_e32 v73, v73
	v_exp_f32_e32 v89, v89
	v_exp_f32_e32 v74, v74
	v_exp_f32_e32 v90, v90
	v_mfma_f32_32x32x16_bf16 v[48:63], v[224:227], v[140:143], v[48:63]
	v_exp_f32_e32 v75, v75
	v_exp_f32_e32 v91, v91
	v_exp_f32_e32 v76, v76
	v_exp_f32_e32 v92, v92
	v_exp_f32_e32 v77, v77
	v_exp_f32_e32 v93, v93
	v_exp_f32_e32 v78, v78
	v_exp_f32_e32 v94, v94
	v_exp_f32_e32 v79, v79
	v_exp_f32_e32 v95, v95
	s_waitcnt lgkmcnt(7)
	ds_read_b64_tr_b16 v[212:213], v178 offset:60160
	ds_read_b64_tr_b16 v[214:215], v178 offset:60672
	ds_read_b64_tr_b16 v[216:217], v178 offset:64256
	ds_read_b64_tr_b16 v[218:219], v178 offset:64768
	ds_read_b64_tr_b16 v[188:189], v178 offset:61184
	ds_read_b64_tr_b16 v[190:191], v178 offset:61696
	ds_read_b64_tr_b16 v[224:225], v178 offset:65280
	ds_read_b64_tr_b16 v[226:227], v251
	v_pk_add_f32 v[238:239], v[84:85], v[68:69]
	v_pk_add_f32 v[240:241], v[80:81], v[64:65]
	v_pk_add_f32 v[242:243], v[86:87], v[70:71]
	v_pk_add_f32 v[244:245], v[82:83], v[66:67]
	s_mov_b64 exec, s[6:7]
	v_cvt_pk_bf16_f32 v156, v64, v65
	v_cvt_pk_bf16_f32 v157, v66, v67
	v_cvt_pk_bf16_f32 v158, v68, v69
	v_cvt_pk_bf16_f32 v159, v70, v71
	s_mov_b64 exec, -1
	v_pk_add_f32 v[246:247], v[90:91], v[74:75]
	v_pk_add_f32 v[248:249], v[88:89], v[72:73]
	s_waitcnt lgkmcnt(14)
	v_mfma_f32_32x32x16_bf16 v[16:31], v[156:159], v[196:199], v[16:31]
	v_pk_add_f32 v[242:243], v[244:245], v[242:243]
	v_pk_add_f32 v[238:239], v[240:241], v[238:239]
	s_mov_b64 exec, s[6:7]
	v_cvt_pk_bf16_f32 v152, v72, v73
	v_cvt_pk_bf16_f32 v153, v74, v75
	v_cvt_pk_bf16_f32 v154, v76, v77
	v_cvt_pk_bf16_f32 v155, v78, v79
	s_mov_b64 exec, -1
	s_waitcnt lgkmcnt(12)
	v_mfma_f32_32x32x16_bf16 v[0:15], v[156:159], v[200:203], v[0:15]
	v_pk_add_f32 v[240:241], v[92:93], v[76:77]
	v_pk_add_f32 v[244:245], v[94:95], v[78:79]
	s_waitcnt lgkmcnt(10)
	v_mfma_f32_32x32x16_bf16 v[16:31], v[152:155], v[204:207], v[16:31]
	v_pk_add_f32 v[248:249], v[248:249], v[238:239]
	v_pk_add_f32 v[246:247], v[246:247], v[242:243]
	s_mov_b64 exec, s[6:7]
	v_cvt_pk_bf16_f32 v148, v80, v81
	v_cvt_pk_bf16_f32 v149, v82, v83
	v_cvt_pk_bf16_f32 v150, v84, v85
	v_cvt_pk_bf16_f32 v151, v86, v87
	s_mov_b64 exec, -1
	s_waitcnt lgkmcnt(8)
	v_mfma_f32_32x32x16_bf16 v[0:15], v[152:155], v[208:211], v[0:15]
	v_pk_add_f32 v[184:185], v[240:241], v[248:249]
	v_pk_add_f32 v[182:183], v[244:245], v[246:247]
	s_waitcnt lgkmcnt(6)
	v_mfma_f32_32x32x16_bf16 v[16:31], v[148:151], v[212:215], v[16:31]
	v_pk_mov_b32 v[186:187], v[184:185], v[182:183] op_sel:[1,0]
	v_mov_b32_e32 v185, v183
	s_mov_b64 exec, s[6:7]
	v_cvt_pk_bf16_f32 v144, v88, v89
	v_cvt_pk_bf16_f32 v145, v90, v91
	v_cvt_pk_bf16_f32 v146, v92, v93
	v_cvt_pk_bf16_f32 v147, v94, v95
	s_mov_b64 exec, -1
	s_waitcnt lgkmcnt(4)
	v_mfma_f32_32x32x16_bf16 v[0:15], v[148:151], v[216:219], v[0:15]
	v_pk_add_f32 v[182:183], v[186:187], v[184:185]
	s_waitcnt lgkmcnt(2)
	v_mfma_f32_32x32x16_bf16 v[16:31], v[144:147], v[188:191], v[16:31]
	v_add_f32_e32 v181, v182, v183
	v_cndmask_b32_e64 v181, 0, v181, s[6:7]
	v_add_f32_e32 v177, v177, v181
	s_waitcnt lgkmcnt(0)
	v_mfma_f32_32x32x16_bf16 v[0:15], v[144:147], v[224:227], v[0:15]
	v_add_u32_e32 v179, 0x4100, v179
	v_add_u32_e32 v178, 0x4000, v178
	s_add_i32 s71, s71, 2
	s_addk_i32 s70, 0x80
	s_branch .LBB0_349
.Lm_rareB:
	v_mov_b32_e32 v144, v238
	s_waitcnt lgkmcnt(0)
	v_mfma_f32_32x32x16_bf16 v[32:47], v[212:215], v[136:139], v[32:47]
	v_mfma_f32_32x32x16_bf16 v[48:63], v[216:219], v[136:139], v[48:63]
	v_mfma_f32_32x32x16_bf16 v[32:47], v[188:191], v[140:143], v[32:47]
	v_mfma_f32_32x32x16_bf16 v[48:63], v[224:227], v[140:143], v[48:63]
	s_branch .Lm_old373

.LBB0_392:
	v_exp_f32_e32 v218, v32
	v_exp_f32_e32 v219, v33
	v_exp_f32_e32 v220, v34
	v_exp_f32_e32 v221, v35
	v_exp_f32_e32 v222, v36
	v_exp_f32_e32 v223, v37
	v_exp_f32_e32 v224, v38
	v_exp_f32_e32 v225, v39
	v_add_u32_e32 v152, 0, v215
	v_add_u32_e32 v217, 0x10300, v152
	v_exp_f32_e32 v226, v40
	v_exp_f32_e32 v227, v41
	v_exp_f32_e32 v232, v42
	v_exp_f32_e32 v233, v43
	v_cvt_pk_bf16_f32 v32, v218, v219
	v_cvt_pk_bf16_f32 v33, v220, v221
	v_cvt_pk_bf16_f32 v34, v222, v223
	v_cvt_pk_bf16_f32 v35, v224, v225
	ds_read_b64_tr_b16 v[36:37], v217
	ds_read_b64_tr_b16 v[38:39], v217 offset:512
	ds_read_b64_tr_b16 v[42:43], v217 offset:4608
	ds_read_b64_tr_b16 v[40:41], v217 offset:4096
	v_exp_f32_e32 v44, v44
	v_exp_f32_e32 v45, v45
	v_exp_f32_e32 v46, v46
	v_exp_f32_e32 v47, v47
	s_waitcnt lgkmcnt(2)
	v_mfma_f32_32x32x16_bf16 v[16:31], v[32:35], v[36:39], v[16:31]
	v_cvt_pk_bf16_f32 v36, v226, v227
	v_cvt_pk_bf16_f32 v37, v232, v233
	v_cvt_pk_bf16_f32 v38, v44, v45
	v_cvt_pk_bf16_f32 v39, v46, v47
	v_exp_f32_e32 v50, v50
	v_exp_f32_e32 v51, v51
	v_exp_f32_e32 v54, v54
	s_waitcnt lgkmcnt(0)
	v_mfma_f32_32x32x16_bf16 v[0:15], v[32:35], v[40:43], v[0:15]
	ds_read_b64_tr_b16 v[32:33], v217 offset:1024
	ds_read_b64_tr_b16 v[34:35], v217 offset:1536
	ds_read_b64_tr_b16 v[40:41], v217 offset:5120
	ds_read_b64_tr_b16 v[42:43], v217 offset:5632
	v_exp_f32_e32 v55, v55
	v_exp_f32_e32 v48, v48
	v_exp_f32_e32 v49, v49
	v_exp_f32_e32 v52, v52
	v_exp_f32_e32 v53, v53
	v_exp_f32_e32 v60, v60
	v_exp_f32_e32 v61, v61
	s_waitcnt lgkmcnt(2)
	v_mfma_f32_32x32x16_bf16 v[16:31], v[36:39], v[32:35], v[16:31]
	v_add_f32_e64 v32, v54, v224
	v_add_f32_e64 v33, v55, v225
	v_add_f32_e64 v34, v50, v220
	v_add_f32_e64 v35, v51, v221
	v_add_f32_e64 v234, v60, v44
	v_add_f32_e64 v235, v61, v45
	v_pk_add_f32 v[44:45], v[34:35], v[32:33]
	v_cvt_pk_bf16_f32 v32, v48, v49
	v_cvt_pk_bf16_f32 v33, v50, v51
	v_cvt_pk_bf16_f32 v34, v52, v53
	s_waitcnt lgkmcnt(0)
	v_mfma_f32_32x32x16_bf16 v[0:15], v[36:39], v[40:43], v[0:15]
	v_cvt_pk_bf16_f32 v35, v54, v55
	ds_read_b64_tr_b16 v[36:37], v217 offset:2048
	ds_read_b64_tr_b16 v[38:39], v217 offset:2560
	ds_read_b64_tr_b16 v[40:41], v217 offset:6144
	ds_read_b64_tr_b16 v[42:43], v217 offset:6656
	v_exp_f32_e32 v56, v56
	v_exp_f32_e32 v57, v57
	v_exp_f32_e32 v58, v58
	v_exp_f32_e32 v62, v62
	v_exp_f32_e32 v63, v63
	v_exp_f32_e32 v59, v59
	s_waitcnt lgkmcnt(2)
	v_mfma_f32_32x32x16_bf16 v[16:31], v[32:35], v[36:39], v[16:31]
	v_add_f32_e64 v222, v52, v222
	v_add_f32_e64 v223, v53, v223
	v_add_f32_e64 v218, v48, v218
	v_add_f32_e64 v219, v49, v219
	v_add_f32_e64 v242, v56, v226
	v_add_f32_e64 v243, v57, v227
	v_pk_add_f32 v[36:37], v[218:219], v[222:223]
	v_pk_add_f32 v[238:239], v[62:63], v[46:47]
	v_pk_add_f32 v[46:47], v[242:243], v[36:37]
	v_cvt_pk_bf16_f32 v36, v56, v57
	s_waitcnt lgkmcnt(0)
	v_mfma_f32_32x32x16_bf16 v[0:15], v[32:35], v[40:43], v[0:15]
	v_cvt_pk_bf16_f32 v37, v58, v59
	v_cvt_pk_bf16_f32 v38, v60, v61
	v_cvt_pk_bf16_f32 v39, v62, v63
	ds_read_b64_tr_b16 v[32:33], v217 offset:3072
	ds_read_b64_tr_b16 v[34:35], v217 offset:3584
	ds_read_b64_tr_b16 v[40:41], v217 offset:7168
	ds_read_b64_tr_b16 v[42:43], v217 offset:7680
	s_waitcnt lgkmcnt(2)
	v_mfma_f32_32x32x16_bf16 v[16:31], v[36:39], v[32:35], v[16:31]
	v_add_f32_e64 v240, v58, v232
	v_add_f32_e64 v241, v59, v233
	v_add_f32_e64 v34, v234, v46
	v_add_f32_e64 v35, v235, v47
	v_add_f32_e64 v44, v240, v44
	v_add_f32_e64 v45, v241, v45
	s_add_i32 s90, s90, 1
	v_pk_add_f32 v[32:33], v[238:239], v[44:45]
	s_add_i32 s92, s92, 64
	v_pk_mov_b32 v[44:45], v[34:35], v[32:33] op_sel:[1,0]
	s_waitcnt lgkmcnt(0)
	v_mfma_f32_32x32x16_bf16 v[0:15], v[36:39], v[40:43], v[0:15]
	v_mov_b32_e32 v35, v33
	v_add_f32_e64 v32, v44, v34
	v_add_f32_e64 v33, v45, v35
	s_sub_i32 s93, s93, 64
	v_add_f32_e32 v32, v32, v33
	v_add_f32_e32 v151, v151, v32
	v_add_u32_e32 v215, 0x2000, v215
	s_cmp_lt_i32 s90, s91
	v_add_u32_e32 v216, 0x2080, v216
	s_cbranch_scc0 .LBB0_402
